# attention loop: hipcc's cndmask+cmp mask inversion replaced by s_not_b64 in the embedded staging code; first four K fragment reads issued before the V-base address math
# baseline (speedup 1.0000x reference)
.LBB0_542:
	s_cmp_gt_u32 s52, s51
	s_cbranch_scc1 .Lh1_skip
	s_mul_i32 s61, s25, 0x2200
	s_and_b32 s42, s52, 2
	s_mulk_i32 s42, 0x3400
	v_add_u32_e32 v0, s42, v160
	ds_read_b128 v[82:85], v0 offset:13312
	ds_read_b128 v[98:101], v0 offset:19968
	ds_read_b128 v[164:167], v0 offset:13344
	ds_read_b128 v[168:171], v0 offset:20000
	v_add_u32_e32 v242, s61, v161
	v_add_u32_e32 v163, 0xe000, v242
	v_add_u32_e32 v242, 0xd000, v242
	ds_read2_b64 v[238:241], v242 offset0:0 offset1:2
	ds_read2_b64 v[234:237], v163 offset0:32 offset1:34
	ds_read_b128 v[172:175], v0 offset:13376
	ds_read_b128 v[176:179], v0 offset:20032
	ds_read_b128 v[180:183], v0 offset:13408
	ds_read_b128 v[184:187], v0 offset:20064
	ds_read_b128 v[188:191], v0 offset:13440
	ds_read_b128 v[192:195], v0 offset:20096
	ds_read_b128 v[196:199], v0 offset:13472
	ds_read_b128 v[220:223], v0 offset:20128
	v_exp_f32_e32 v50, v50
	v_exp_f32_e32 v51, v51
	v_exp_f32_e32 v52, v52
	v_exp_f32_e32 v53, v53
	v_exp_f32_e32 v54, v54
	v_exp_f32_e32 v55, v55
	v_exp_f32_e32 v56, v56
	v_exp_f32_e32 v57, v57
	s_waitcnt lgkmcnt(13)
	v_mfma_f32_32x32x16_bf16 v[82:97], v[82:85], v[122:125], 0
	v_cvt_pk_bf16_f32 v224, v50, v51
	v_cvt_pk_bf16_f32 v225, v52, v53
	v_cvt_pk_bf16_f32 v226, v54, v55
	v_cvt_pk_bf16_f32 v227, v56, v57
	v_exp_f32_e32 v58, v58
	v_add_f32_e32 v200, v50, v51
	s_waitcnt lgkmcnt(12)
	v_mfma_f32_32x32x16_bf16 v[98:113], v[98:101], v[122:125], 0
	v_exp_f32_e32 v59, v59
	v_exp_f32_e32 v60, v60
	v_add_f32_e32 v201, v52, v53
	v_exp_f32_e32 v61, v61
	s_add_i32 s60, s52, 3
	s_cmp_lt_u32 s60, s48
	s_cselect_b64 s[58:59], -1, 0
	s_cmp_ge_u32 s60, s48
	s_cbranch_scc1 .Lp1a_546
	s_waitcnt vmcnt(0)
	v_lshl_add_u64 v[2:3], s[54:55], 0, v[154:155]
	v_add_co_u32_e32 v2, vcc, 0xbe09000, v2
	s_nop 1
	v_addc_co_u32_e32 v3, vcc, 0, v3, vcc
	global_load_dwordx4 v[2:5], v[2:3], off
	s_and_saveexec_b64 s[42:43], s[40:41]
	s_cbranch_execz .Lp1a_545
	v_lshl_add_u64 v[10:11], s[54:55], 0, v[152:153]
	v_add_co_u32_e32 v10, vcc, 0xbe09000, v10
	s_nop 1
	v_addc_co_u32_e32 v11, vcc, 0, v11, vcc
	global_load_dwordx4 v[10:13], v[10:11], off

.Lp1a_end:
	s_waitcnt lgkmcnt(11)
	v_mfma_f32_32x32x16_bf16 v[82:97], v[164:167], v[126:129], v[82:97]
	v_exp_f32_e32 v62, v62
	v_add_f32_e32 v200, v200, v54
	v_exp_f32_e32 v63, v63
	v_add_f32_e32 v201, v201, v55
	v_exp_f32_e32 v64, v64
	s_waitcnt lgkmcnt(10)
	v_mfma_f32_32x32x16_bf16 v[98:113], v[168:171], v[126:129], v[98:113]
	ds_read2_b64 v[164:167], v242 offset0:4 offset1:6
	ds_read2_b64 v[168:171], v163 offset0:36 offset1:38
	v_add_f32_e32 v200, v200, v56
	v_exp_f32_e32 v65, v65
	v_add_f32_e32 v201, v201, v57
	v_cvt_pk_bf16_f32 v228, v58, v59
	v_cvt_pk_bf16_f32 v229, v60, v61
	s_waitcnt lgkmcnt(11)
	v_mfma_f32_32x32x16_bf16 v[18:33], v[238:241], v[224:227], v[18:33]
	v_cvt_pk_bf16_f32 v230, v62, v63
	v_cvt_pk_bf16_f32 v231, v64, v65
	v_exp_f32_e32 v66, v66
	v_add_f32_e32 v200, v200, v58
	v_exp_f32_e32 v67, v67
	v_add_f32_e32 v201, v201, v59
	s_waitcnt lgkmcnt(10)
	v_mfma_f32_32x32x16_bf16 v[34:49], v[234:237], v[224:227], v[34:49]
	v_exp_f32_e32 v68, v68
	v_add_f32_e32 v200, v200, v60
	v_exp_f32_e32 v69, v69
	v_add_f32_e32 v201, v201, v61
	v_exp_f32_e32 v70, v70
	s_waitcnt lgkmcnt(9)
	v_mfma_f32_32x32x16_bf16 v[82:97], v[172:175], v[134:137], v[82:97]
	v_add_f32_e32 v200, v200, v62
	v_exp_f32_e32 v71, v71
	v_add_f32_e32 v201, v201, v63
	v_exp_f32_e32 v72, v72
	v_add_f32_e32 v200, v200, v64
	s_waitcnt lgkmcnt(8)
	v_mfma_f32_32x32x16_bf16 v[98:113], v[176:179], v[134:137], v[98:113]
	ds_read2_b64 v[172:175], v242 offset0:8 offset1:10
	ds_read2_b64 v[176:179], v163 offset0:40 offset1:42
	v_exp_f32_e32 v73, v73
	v_add_f32_e32 v201, v201, v65
	v_cvt_pk_bf16_f32 v224, v66, v67
	v_cvt_pk_bf16_f32 v225, v68, v69
	v_cvt_pk_bf16_f32 v226, v70, v71
	s_waitcnt lgkmcnt(3)
	v_mfma_f32_32x32x16_bf16 v[18:33], v[164:167], v[228:231], v[18:33]
	v_cvt_pk_bf16_f32 v227, v72, v73
	v_exp_f32_e32 v74, v74
	v_add_f32_e32 v200, v200, v66
	v_exp_f32_e32 v75, v75
	v_add_f32_e32 v201, v201, v67
	s_waitcnt lgkmcnt(2)
	v_mfma_f32_32x32x16_bf16 v[34:49], v[168:171], v[228:231], v[34:49]
	v_exp_f32_e32 v76, v76
	v_add_f32_e32 v200, v200, v68
	v_exp_f32_e32 v77, v77
	v_add_f32_e32 v201, v201, v69
	v_exp_f32_e32 v78, v78
	s_waitcnt lgkmcnt(9)
	v_mfma_f32_32x32x16_bf16 v[82:97], v[180:183], v[138:141], v[82:97]
	v_add_f32_e32 v200, v200, v70
	v_exp_f32_e32 v79, v79
	v_add_f32_e32 v201, v201, v71
	v_exp_f32_e32 v80, v80
	v_add_f32_e32 v200, v200, v72
	s_waitcnt lgkmcnt(8)
	v_mfma_f32_32x32x16_bf16 v[98:113], v[184:187], v[138:141], v[98:113]
	ds_read2_b64 v[180:183], v242 offset0:12 offset1:14
	ds_read2_b64 v[184:187], v163 offset0:44 offset1:46
	v_exp_f32_e32 v81, v81
	v_add_f32_e32 v201, v201, v73
	v_cvt_pk_bf16_f32 v228, v74, v75
	v_cvt_pk_bf16_f32 v229, v76, v77
	v_cvt_pk_bf16_f32 v230, v78, v79
	s_waitcnt lgkmcnt(3)
	v_mfma_f32_32x32x16_bf16 v[18:33], v[172:175], v[224:227], v[18:33]
	v_cvt_pk_bf16_f32 v231, v80, v81
	v_add_f32_e32 v200, v200, v74
	v_add_f32_e32 v201, v201, v75
	v_add_f32_e32 v200, v200, v76
	v_add_f32_e32 v201, v201, v77
	v_add_f32_e32 v200, v200, v78
	v_add_f32_e32 v201, v201, v79
	v_add_f32_e32 v200, v200, v80
	s_waitcnt lgkmcnt(2)
	v_mfma_f32_32x32x16_bf16 v[34:49], v[176:179], v[224:227], v[34:49]
	v_add_f32_e32 v201, v201, v81
	v_add_f32_e32 v200, v200, v201
	v_add_f32_e32 v162, v162, v200
	s_waitcnt lgkmcnt(9)
	v_mfma_f32_32x32x16_bf16 v[82:97], v[188:191], v[142:145], v[82:97]
	s_waitcnt lgkmcnt(8)
	v_mfma_f32_32x32x16_bf16 v[98:113], v[192:195], v[142:145], v[98:113]
	s_waitcnt lgkmcnt(7)
	v_mfma_f32_32x32x16_bf16 v[82:97], v[196:199], v[146:149], v[82:97]
	s_waitcnt lgkmcnt(6)
	v_mfma_f32_32x32x16_bf16 v[98:113], v[220:223], v[146:149], v[98:113]
	s_waitcnt lgkmcnt(0)
	s_not_b64 s[42:43], s[44:45]
	s_andn2_b64 vcc, exec, s[44:45]
	s_cbranch_vccnz .Lt1a_mid
	s_and_b32 s44, s53, 2
	s_mulk_i32 s44, 0x3400
	s_add_i32 s62, s44, 0
	v_add_u32_e32 v0, s62, v151
	s_waitcnt vmcnt(0)
	ds_write_b128 v0, v[118:121]
	s_and_saveexec_b64 s[44:45], s[40:41]
	v_add_u32_e32 v0, s62, v159
	ds_write_b128 v0, v[6:9]
	s_or_b64 exec, exec, s[44:45]

.LBB0_556:
	s_add_i32 s61, s25, 1
	s_cmp_lg_u32 s25, 2
	s_cselect_b32 s25, s61, 0
	s_andn2_b64 vcc, exec, s[44:45]
	s_waitcnt lgkmcnt(0)
	s_barrier
	s_cbranch_vccnz .LBB0_572
	s_cmp_ge_u32 s52, s51
	s_cbranch_scc1 .Lh2_skip
	s_andn2_b32 s62, 2, s52
	s_mulk_i32 s62, 0x3400
	v_add_u32_e32 v0, s62, v160
	ds_read_b128 v[50:53], v0 offset:0
	ds_read_b128 v[66:69], v0 offset:6656
	ds_read_b128 v[164:167], v0 offset:32
	ds_read_b128 v[168:171], v0 offset:6688
	s_mul_i32 s62, s25, 0x2200
	v_add_u32_e32 v242, s62, v161
	v_add_u32_e32 v163, 0xe000, v242
	v_add_u32_e32 v242, 0xd000, v242
	ds_read2_b64 v[238:241], v242 offset0:0 offset1:2
	ds_read2_b64 v[234:237], v163 offset0:32 offset1:34
	ds_read_b128 v[172:175], v0 offset:64
	ds_read_b128 v[176:179], v0 offset:6720
	ds_read_b128 v[180:183], v0 offset:96
	ds_read_b128 v[184:187], v0 offset:6752
	ds_read_b128 v[188:191], v0 offset:128
	ds_read_b128 v[192:195], v0 offset:6784
	ds_read_b128 v[196:199], v0 offset:160
	ds_read_b128 v[220:223], v0 offset:6816
	v_exp_f32_e32 v82, v82
	v_exp_f32_e32 v83, v83
	v_exp_f32_e32 v84, v84
	v_exp_f32_e32 v85, v85
	v_exp_f32_e32 v86, v86
	v_exp_f32_e32 v87, v87
	v_exp_f32_e32 v88, v88
	v_exp_f32_e32 v89, v89
	s_waitcnt lgkmcnt(13)
	v_mfma_f32_32x32x16_bf16 v[50:65], v[50:53], v[122:125], 0
	v_cvt_pk_bf16_f32 v224, v82, v83
	v_cvt_pk_bf16_f32 v225, v84, v85
	v_cvt_pk_bf16_f32 v226, v86, v87
	v_cvt_pk_bf16_f32 v227, v88, v89
	v_exp_f32_e32 v90, v90
	v_add_f32_e32 v200, v82, v83
	s_waitcnt lgkmcnt(12)
	v_mfma_f32_32x32x16_bf16 v[66:81], v[66:69], v[122:125], 0
	v_exp_f32_e32 v91, v91
	v_exp_f32_e32 v92, v92
	v_add_f32_e32 v201, v84, v85
	v_exp_f32_e32 v93, v93
	s_cmp_ge_u32 s52, s5
	s_cbranch_scc1 .Lp2a_561
	s_waitcnt vmcnt(0)
	v_lshl_add_u64 v[118:119], s[54:55], 0, v[154:155]
	v_add_co_u32_e32 v118, vcc, 0xbe0c000, v118
	s_nop 1
	v_addc_co_u32_e32 v119, vcc, 0, v119, vcc
	global_load_dwordx4 v[118:121], v[118:119], off
	s_and_saveexec_b64 s[44:45], s[40:41]
	s_cbranch_execz .Lp2a_560
	v_lshl_add_u64 v[6:7], s[54:55], 0, v[152:153]
	v_add_co_u32_e32 v6, vcc, 0xbe0c000, v6
	s_nop 1
	v_addc_co_u32_e32 v7, vcc, 0, v7, vcc
	global_load_dwordx4 v[6:9], v[6:7], off

.Lp2a_561:
	s_not_b64 s[44:45], s[58:59]
	s_andn2_b64 vcc, exec, s[58:59]
	s_cbranch_vccnz .Lp2a_end
	global_load_dwordx4 v[130:133], v[156:157], off offset:128
